# GQA sample loop software-pipelined: QK of tile t+1 interleaved with exp/cvt of tile t (two S register sets), 3 LDS buffers, 4 staging sets, VALU row sums
# baseline (speedup 1.0000x reference)
.LBB0_1175:
	s_waitcnt vmcnt(0)
	s_nop 11
	v_add_f32_e32 v32, v198, v199
	v_add_f32_e32 v33, v248, v249
	v_add_f32_e32 v32, v32, v33
	v_mov_b32_e32 v33, v32
	s_nop 1
	v_permlane32_swap_b32_e32 v32, v33
	v_add_f32_e32 v32, v32, v33
	v_div_scale_f32 v33, s[0:1], v32, v32, 1.0
	v_rcp_f32_e32 v34, v33
	v_mov_b32_e32 v91, v131
	v_fma_f32 v35, -v33, v34, 1.0
	v_fmac_f32_e32 v34, v35, v34
	v_div_scale_f32 v35, vcc, 1.0, v32, 1.0
	v_mul_f32_e32 v36, v35, v34
	v_fma_f32 v37, -v33, v36, v35
	v_fmac_f32_e32 v36, v37, v34
	v_fma_f32 v33, -v33, v36, v35
	v_div_fmas_f32 v33, v33, v34, v36
	v_div_fixup_f32 v32, v33, v32, 1.0
	s_barrier
	v_lshlrev_b32_e32 v36, 1, v90
	v_mov_b32_e32 v37, 0
	v_lshl_add_u64 v[36:37], v[88:89], 0, v[36:37]
	v_pk_mul_f32 v[0:1], v[0:1], v[32:33] op_sel_hi:[1,0]
	v_pk_mul_f32 v[2:3], v[2:3], v[32:33] op_sel_hi:[1,0]
	v_pk_mul_f32 v[4:5], v[4:5], v[32:33] op_sel_hi:[1,0]
	v_pk_mul_f32 v[6:7], v[6:7], v[32:33] op_sel_hi:[1,0]
	v_cvt_pk_bf16_f32 v0, v0, v1
	v_cvt_pk_bf16_f32 v1, v2, v3
	v_cvt_pk_bf16_f32 v2, v4, v5
	v_cvt_pk_bf16_f32 v3, v6, v7
	s_nop 1
	v_permlane32_swap_b32_e32 v0, v2
	v_permlane32_swap_b32_e32 v1, v3
	global_store_dwordx4 v[36:37], v[0:3], off
	v_pk_mul_f32 v[8:9], v[8:9], v[32:33] op_sel_hi:[1,0]
	v_pk_mul_f32 v[10:11], v[10:11], v[32:33] op_sel_hi:[1,0]
	v_pk_mul_f32 v[12:13], v[12:13], v[32:33] op_sel_hi:[1,0]
	v_pk_mul_f32 v[14:15], v[14:15], v[32:33] op_sel_hi:[1,0]
	v_cvt_pk_bf16_f32 v8, v8, v9
	v_cvt_pk_bf16_f32 v9, v10, v11
	v_cvt_pk_bf16_f32 v10, v12, v13
	v_cvt_pk_bf16_f32 v11, v14, v15
	s_nop 1
	v_permlane32_swap_b32_e32 v8, v10
	v_permlane32_swap_b32_e32 v9, v11
	global_store_dwordx4 v[36:37], v[8:11], off offset:32
	v_pk_mul_f32 v[16:17], v[16:17], v[32:33] op_sel_hi:[1,0]
	v_pk_mul_f32 v[18:19], v[18:19], v[32:33] op_sel_hi:[1,0]
	v_pk_mul_f32 v[20:21], v[20:21], v[32:33] op_sel_hi:[1,0]
	v_pk_mul_f32 v[22:23], v[22:23], v[32:33] op_sel_hi:[1,0]
	v_cvt_pk_bf16_f32 v16, v16, v17
	v_cvt_pk_bf16_f32 v17, v18, v19
	v_cvt_pk_bf16_f32 v18, v20, v21
	v_cvt_pk_bf16_f32 v19, v22, v23
	s_nop 1
	v_permlane32_swap_b32_e32 v16, v18
	v_permlane32_swap_b32_e32 v17, v19
	global_store_dwordx4 v[36:37], v[16:19], off offset:64
	v_pk_mul_f32 v[24:25], v[24:25], v[32:33] op_sel_hi:[1,0]
	v_pk_mul_f32 v[26:27], v[26:27], v[32:33] op_sel_hi:[1,0]
	v_pk_mul_f32 v[28:29], v[28:29], v[32:33] op_sel_hi:[1,0]
	v_pk_mul_f32 v[30:31], v[30:31], v[32:33] op_sel_hi:[1,0]
	v_cvt_pk_bf16_f32 v24, v24, v25
	v_cvt_pk_bf16_f32 v25, v26, v27
	v_cvt_pk_bf16_f32 v26, v28, v29
	v_cvt_pk_bf16_f32 v27, v30, v31
	s_nop 1
	v_permlane32_swap_b32_e32 v24, v26
	v_permlane32_swap_b32_e32 v25, v27
	global_store_dwordx4 v[36:37], v[24:27], off offset:96

.LBB0_1197:
	s_lshl_b32 s5, s0, 8
	s_lshl_b32 s4, s1, 12
	s_and_b32 s5, s5, 0xf00
	s_or_b32 s4, s4, s5
	s_addk_i32 s4, 0x2000
	s_and_b32 s3, s3, 1
	s_mul_hi_i32 s5, s4, 0x1600
	s_mulk_i32 s4, 0x1600
	v_readlane_b32 s6, v254, 62
	v_readlane_b32 s7, v254, 63
	s_add_u32 s6, s6, s4
	s_addc_u32 s7, s7, s5
	s_lshl_b32 s0, s0, 2
	s_lshl_b32 s4, s3, 8
	s_andn2_b32 s0, s0, 63
	s_add_i32 s26, s4, s0
	s_lshl_b64 s[4:5], s[26:27], 1
	s_add_u32 s0, s6, s4
	s_addc_u32 s4, s7, s5
	s_add_u32 s6, s0, 0x1000
	s_addc_u32 s7, s4, 0
	s_mul_i32 s4, s1, 0x110000
	v_readlane_b32 s8, v255, 35
	s_mul_hi_i32 s0, s1, 0x110000
	v_readlane_b32 s9, v255, 36
	s_add_u32 s4, s8, s4
	s_addc_u32 s0, s9, s0
	s_lshl_b32 s5, s3, 6
	s_lshl_b32 s3, s3, 7
	s_add_u32 s8, s4, s3
	s_addc_u32 s9, s0, 0
	s_lshl_b32 s0, s1, 7
	s_or_b32 s0, s0, s5
	s_mul_i32 s4, s0, 0x2200
	v_readlane_b32 s10, v255, 39
	v_mov_b32_e32 v20, v128
	s_mul_hi_i32 s5, s0, 0x2200
	v_readlane_b32 s11, v255, 40
	s_add_u32 s10, s10, s4
	s_addc_u32 s11, s11, s5
	v_readfirstlane_b32 s0, v20
	s_ashr_i32 s0, s0, 1
	v_bfe_u32 v21, v20, 5, 1
	v_mov_b32_e32 v0, s0
	s_movk_i32 s0, 0xffe0
	v_bfi_b32 v2, s0, v0, v20
	v_mov_b64_e32 v[0:1], s[6:7]
	s_movk_i32 s0, 0x1600
	v_ashrrev_i32_e32 v16, 3, v20
	v_mad_i64_i32 v[88:89], s[6:7], v2, s0, v[0:1]
	v_lshlrev_b32_e32 v130, 4, v21
	v_lshlrev_b32_e32 v22, 3, v20
	v_ashrrev_i32_e32 v17, 31, v16
	v_lshl_add_u64 v[0:1], v[88:89], 0, v[130:131]
	v_and_b32_e32 v23, 56, v22
	v_lshlrev_b64 v[18:19], 8, v[16:17]
	global_load_dwordx4 v[76:79], v[0:1], off
	global_load_dwordx4 v[72:75], v[0:1], off offset:32
	global_load_dwordx4 v[68:71], v[0:1], off offset:64
	global_load_dwordx4 v[64:67], v[0:1], off offset:96
	v_lshl_add_u64 v[0:1], s[8:9], 0, v[18:19]
	v_lshlrev_b32_e32 v2, 1, v23
	v_mov_b32_e32 v3, v131
	v_mov_b64_e32 v[4:5], s[10:11]
	s_movk_i32 s8, 0x2200
	v_lshl_add_u64 v[0:1], v[0:1], 0, v[2:3]
	v_mad_i64_i32 v[4:5], s[6:7], v16, s8, v[4:5]
	s_waitcnt vmcnt(63) expcnt(7) lgkmcnt(15)
	s_barrier
	v_lshl_add_u64 v[2:3], v[4:5], 0, v[2:3]
	global_load_dwordx4 v[8:11], v[0:1], off
	global_load_dwordx4 v[12:15], v[2:3], off
	s_movk_i32 s6, 0x48
	v_and_b32_e32 v17, 31, v20
	v_lshlrev_b32_e32 v90, 3, v21
	v_mul_lo_u32 v21, v16, s6
	v_and_b32_e32 v22, 48, v22
	v_lshlrev_b32_e32 v24, 2, v20
	v_lshlrev_b32_e32 v20, 4, v20
	v_mul_u32_u24_e32 v25, 0x48, v17
	v_mul_u32_u24_e32 v93, 0x90, v17
	v_add_u32_e32 v17, v21, v22
	v_mad_i64_i32 v[18:19], s[6:7], s1, v180, v[18:19]
	v_and_b32_e32 v20, 0x70, v20
	v_and_or_b32 v17, v24, 4, v17
	v_readlane_b32 s6, v253, 16
	v_lshlrev_b32_e32 v100, 1, v17
	v_or3_b32 v18, v18, s3, v20
	v_readlane_b32 s7, v253, 17
	v_add_u32_e32 v17, 0, v100
	v_add_lshl_u32 v98, v21, v23, 1
	v_lshl_add_u64 v[94:95], s[6:7], 0, v[18:19]
	v_mov_b64_e32 v[18:19], s[4:5]
	v_add_u32_e32 v22, 0x2000, v17
	v_mad_i64_i32 v[16:17], s[4:5], v16, s8, v[18:19]
	v_add_u32_e32 v21, 0, v98
	v_readlane_b32 s4, v253, 12
	v_or_b32_e32 v16, v16, v20
	v_readlane_b32 s5, v253, 13
	v_mov_b32_e32 v0, v131
	v_mov_b32_e32 v1, v131
	v_mov_b32_e32 v2, v131
	v_mov_b32_e32 v3, v131
	v_mov_b32_e32 v4, v131
	v_mov_b32_e32 v5, v131
	v_mov_b32_e32 v6, v131
	s_waitcnt vmcnt(1)
	ds_write_b128 v21, v[8:11]
	s_waitcnt vmcnt(0)
	ds_write2_b64 v22, v[12:13], v[14:15] offset0:128 offset1:130
	v_mov_b32_e32 v14, v131
	v_mov_b32_e32 v15, v131
	v_mov_b32_e32 v7, v131
	v_add_lshl_u32 v99, v90, v25, 1
	v_lshl_add_u64 v[96:97], s[4:5], 0, v[16:17]
	v_mov_b32_e32 v8, v131
	v_mov_b32_e32 v9, v131
	v_mov_b32_e32 v10, v131
	v_mov_b32_e32 v11, v131
	v_mov_b32_e32 v12, v131
	v_mov_b32_e32 v13, v131
	v_mov_b64_e32 v[30:31], v[14:15]
	s_mov_b32 s0, 0
	v_mov_b32_e32 v91, 0
	v_mov_b32_e32 v92, 0xff800000
	v_mov_b64_e32 v[28:29], v[12:13]
	v_mov_b64_e32 v[26:27], v[10:11]
	v_mov_b64_e32 v[24:25], v[8:9]
	v_mov_b64_e32 v[22:23], v[6:7]
	v_mov_b64_e32 v[20:21], v[4:5]
	v_mov_b64_e32 v[18:19], v[2:3]
	v_mov_b64_e32 v[16:17], v[0:1]
	global_load_dwordx4 v[112:115], v[94:95], off
	global_load_dwordx4 v[116:119], v[96:97], off
	s_mov_b64 s[4:5], 0x4000
	s_nop 0
	v_lshl_add_u64 v[94:95], v[94:95], 0, s[4:5]
	v_lshl_add_u64 v[96:97], v[96:97], 0, s[30:31]
	global_load_dwordx4 v[120:123], v[94:95], off
	global_load_dwordx4 v[124:127], v[96:97], off
	v_lshl_add_u64 v[94:95], v[94:95], 0, s[4:5]
	v_lshl_add_u64 v[96:97], v[96:97], 0, s[30:31]
	global_load_dwordx4 v[208:211], v[94:95], off
	global_load_dwordx4 v[212:215], v[96:97], off
	v_lshl_add_u64 v[94:95], v[94:95], 0, s[4:5]
	v_lshl_add_u64 v[96:97], v[96:97], 0, s[30:31]
	global_load_dwordx4 v[200:203], v[94:95], off
	global_load_dwordx4 v[204:207], v[96:97], off
	v_lshl_add_u64 v[94:95], v[94:95], 0, s[4:5]
	v_lshl_add_u64 v[96:97], v[96:97], 0, s[30:31]
	s_mov_b32 s61, 0x53800000
	s_mov_b64 s[62:63], 0
	s_mov_b64 s[64:65], 0
	v_add_u32_e32 v170, 0x2000, v100
	s_waitcnt lgkmcnt(0)
	s_barrier
	v_add_u32_e32 v101, 0, v99
	ds_read_b128 v[182:185], v101
	ds_read_b128 v[186:189], v101 offset:32
	ds_read_b128 v[190:193], v101 offset:64
	ds_read_b128 v[194:197], v101 offset:96
	s_waitcnt lgkmcnt(3)
	v_mfma_f32_32x32x16_bf16 v[48:63], v[182:185], v[76:79], 0
	ds_read_b128 v[182:185], v101 offset:4608
	s_waitcnt lgkmcnt(3)
	v_mfma_f32_32x32x16_bf16 v[48:63], v[186:189], v[72:75], v[48:63]
	ds_read_b128 v[186:189], v101 offset:4640
	s_waitcnt lgkmcnt(3)
	v_mfma_f32_32x32x16_bf16 v[48:63], v[190:193], v[68:71], v[48:63]
	ds_read_b128 v[190:193], v101 offset:4672
	s_waitcnt lgkmcnt(3)
	v_mfma_f32_32x32x16_bf16 v[48:63], v[194:197], v[64:67], v[48:63]
	ds_read_b128 v[194:197], v101 offset:4704
	s_waitcnt lgkmcnt(3)
	v_mfma_f32_32x32x16_bf16 v[32:47], v[182:185], v[76:79], 0
	s_waitcnt lgkmcnt(2)
	v_mfma_f32_32x32x16_bf16 v[32:47], v[186:189], v[72:75], v[32:47]
	s_waitcnt lgkmcnt(1)
	v_mfma_f32_32x32x16_bf16 v[32:47], v[190:193], v[68:71], v[32:47]
	s_waitcnt lgkmcnt(0)
	v_mfma_f32_32x32x16_bf16 v[32:47], v[194:197], v[64:67], v[32:47]
	s_nop 11
	v_max_f32_e32 v101, v32, v48
	v_max3_f32 v101, v101, v49, v33
	v_max3_f32 v101, v101, v50, v34
	v_max3_f32 v101, v101, v51, v35
	v_max3_f32 v101, v101, v52, v36
	v_max3_f32 v101, v101, v53, v37
	v_max3_f32 v101, v101, v54, v38
	v_max3_f32 v101, v101, v55, v39
	v_max3_f32 v101, v101, v56, v40
	v_max3_f32 v101, v101, v57, v41
	v_max3_f32 v101, v101, v58, v42
	v_max3_f32 v101, v101, v59, v43
	v_max3_f32 v101, v101, v60, v44
	v_max3_f32 v101, v101, v61, v45
	v_max3_f32 v101, v101, v62, v46
	v_max3_f32 v101, v101, v63, v47
	v_mov_b32_e32 v102, v101
	s_nop 1
	v_permlane32_swap_b32_e32 v101, v102
	v_max_f32_e32 v101, v101, v102
	v_mul_f32_e32 v182, -1.0, v101
	v_mov_b32_e32 v183, v182
	v_mov_b32_e32 v184, v182
	v_mov_b32_e32 v185, v182
	v_mov_b32_e32 v186, v182
	v_mov_b32_e32 v187, v182
	v_mov_b32_e32 v188, v182
	v_mov_b32_e32 v189, v182
	v_mov_b32_e32 v190, v182
	v_mov_b32_e32 v191, v182
	v_mov_b32_e32 v192, v182
	v_mov_b32_e32 v193, v182
	v_mov_b32_e32 v194, v182
	v_mov_b32_e32 v195, v182
	v_mov_b32_e32 v196, v182
	v_mov_b32_e32 v197, v182
	v_add_f32_e32 v48, v48, v182
	v_add_f32_e32 v49, v49, v182
	v_add_f32_e32 v50, v50, v182
	v_add_f32_e32 v51, v51, v182
	v_add_f32_e32 v52, v52, v182
	v_add_f32_e32 v53, v53, v182
	v_add_f32_e32 v54, v54, v182
	v_add_f32_e32 v55, v55, v182
	v_add_f32_e32 v56, v56, v182
	v_add_f32_e32 v57, v57, v182
	v_add_f32_e32 v58, v58, v182
	v_add_f32_e32 v59, v59, v182
	v_add_f32_e32 v60, v60, v182
	v_add_f32_e32 v61, v61, v182
	v_add_f32_e32 v62, v62, v182
	v_add_f32_e32 v63, v63, v182
	v_add_f32_e32 v32, v32, v182
	v_add_f32_e32 v33, v33, v182
	v_add_f32_e32 v34, v34, v182
	v_add_f32_e32 v35, v35, v182
	v_add_f32_e32 v36, v36, v182
	v_add_f32_e32 v37, v37, v182
	v_add_f32_e32 v38, v38, v182
	v_add_f32_e32 v39, v39, v182
	v_add_f32_e32 v40, v40, v182
	v_add_f32_e32 v41, v41, v182
	v_add_f32_e32 v42, v42, v182
	v_add_f32_e32 v43, v43, v182
	v_add_f32_e32 v44, v44, v182
	v_add_f32_e32 v45, v45, v182
	v_add_f32_e32 v46, v46, v182
	v_add_f32_e32 v47, v47, v182
	v_mov_b32_e32 v198, 0
	v_mov_b32_e32 v199, 0
	v_mov_b32_e32 v248, 0
	v_mov_b32_e32 v249, 0
	v_add_u32_e32 v91, 0x4800, v98
	v_add_u32_e32 v92, 0x4800, v170
	s_waitcnt vmcnt(6)
	ds_write_b128 v91, v[112:115]
	ds_write2_b64 v92, v[116:117], v[118:119] offset0:128 offset1:130
	s_waitcnt lgkmcnt(0)
	global_load_dwordx4 v[112:115], v[94:95], off
	global_load_dwordx4 v[116:119], v[96:97], off
	v_lshl_add_u64 v[94:95], v[94:95], 0, s[4:5]
	v_lshl_add_u64 v[96:97], v[96:97], 0, s[30:31]
	s_mov_b32 s66, 0
	s_movk_i32 s67, 0x4800
	s_mov_b32 s68, 0x9000
	s_barrier
.Lgqa_c0:
	v_lshl_add_u64 v[94:95], v[94:95], 0, s[62:63]
	v_lshl_add_u64 v[96:97], v[96:97], 0, s[64:65]
	v_add_u32_e32 v101, s67, v99
	v_add3_u32 v102, s66, v93, v130
	v_max3_f32 v91, v198, v199, v248
	v_max_f32_e32 v91, v91, v249
	v_cmp_lt_f32_e32 vcc, s61, v91
	s_cbranch_vccnz .Lgqa_rare0
.Lgqa_rb0:
	ds_read_b128 v[80:83], v101
	ds_read_b128 v[84:87], v101 offset:32
	ds_read_b128 v[104:107], v101 offset:64
	ds_read_b128 v[108:111], v101 offset:96
	v_exp_f32_e32 v48, v48
	v_exp_f32_e32 v49, v49
	v_exp_f32_e32 v50, v50
	v_exp_f32_e32 v51, v51
	v_exp_f32_e32 v52, v52
	v_exp_f32_e32 v53, v53
	v_exp_f32_e32 v54, v54
	v_exp_f32_e32 v55, v55
	v_add_f32_e32 v198, v198, v48
	v_add_f32_e32 v199, v199, v49
	v_add_f32_e32 v248, v248, v50
	v_add_f32_e32 v249, v249, v51
	v_add_f32_e32 v198, v198, v52
	v_add_f32_e32 v199, v199, v53
	v_add_f32_e32 v248, v248, v54
	v_add_f32_e32 v249, v249, v55
	s_waitcnt lgkmcnt(3)
	v_mfma_f32_32x32x16_bf16 v[232:247], v[80:83], v[76:79], v[182:197]
	ds_read_b128 v[80:83], v101 offset:4608
	v_cvt_pk_bf16_f32 v48, v48, v49
	v_cvt_pk_bf16_f32 v49, v50, v51
	v_cvt_pk_bf16_f32 v50, v52, v53
	v_cvt_pk_bf16_f32 v51, v54, v55
	s_waitcnt lgkmcnt(3)
	v_mfma_f32_32x32x16_bf16 v[232:247], v[84:87], v[72:75], v[232:247]
	ds_read_b128 v[84:87], v101 offset:4640
	v_exp_f32_e32 v56, v56
	v_exp_f32_e32 v57, v57
	v_exp_f32_e32 v58, v58
	v_exp_f32_e32 v59, v59
	s_waitcnt lgkmcnt(3)
	v_mfma_f32_32x32x16_bf16 v[232:247], v[104:107], v[68:71], v[232:247]
	ds_read_b128 v[104:107], v101 offset:4672
	v_exp_f32_e32 v60, v60
	v_exp_f32_e32 v61, v61
	v_exp_f32_e32 v62, v62
	v_exp_f32_e32 v63, v63
	s_waitcnt lgkmcnt(3)
	v_mfma_f32_32x32x16_bf16 v[232:247], v[108:111], v[64:67], v[232:247]
	ds_read_b128 v[108:111], v101 offset:4704
	v_add_f32_e32 v198, v198, v56
	v_add_f32_e32 v199, v199, v57
	v_add_f32_e32 v248, v248, v58
	v_add_f32_e32 v249, v249, v59
	v_add_f32_e32 v198, v198, v60
	v_add_f32_e32 v199, v199, v61
	v_add_f32_e32 v248, v248, v62
	v_add_f32_e32 v249, v249, v63
	s_waitcnt lgkmcnt(3)
	v_mfma_f32_32x32x16_bf16 v[216:231], v[80:83], v[76:79], v[182:197]
	ds_read_b128 v[80:83], v102 offset:9216
	v_cvt_pk_bf16_f32 v56, v56, v57
	v_cvt_pk_bf16_f32 v57, v58, v59
	v_cvt_pk_bf16_f32 v58, v60, v61
	v_cvt_pk_bf16_f32 v59, v62, v63
	s_waitcnt lgkmcnt(3)
	v_mfma_f32_32x32x16_bf16 v[216:231], v[84:87], v[72:75], v[216:231]
	ds_read_b128 v[84:87], v102 offset:13824
	v_exp_f32_e32 v32, v32
	v_exp_f32_e32 v33, v33
	v_exp_f32_e32 v34, v34
	v_exp_f32_e32 v35, v35
	s_waitcnt lgkmcnt(3)
	v_mfma_f32_32x32x16_bf16 v[216:231], v[104:107], v[68:71], v[216:231]
	ds_read_b128 v[104:107], v102 offset:9248
	v_exp_f32_e32 v36, v36
	v_exp_f32_e32 v37, v37
	v_exp_f32_e32 v38, v38
	v_exp_f32_e32 v39, v39
	s_waitcnt lgkmcnt(3)
	v_mfma_f32_32x32x16_bf16 v[216:231], v[108:111], v[64:67], v[216:231]
	ds_read_b128 v[108:111], v102 offset:13856
	v_add_f32_e32 v198, v198, v32
	v_add_f32_e32 v199, v199, v33
	v_add_f32_e32 v248, v248, v34
	v_add_f32_e32 v249, v249, v35
	v_add_f32_e32 v198, v198, v36
	v_add_f32_e32 v199, v199, v37
	v_add_f32_e32 v248, v248, v38
	v_add_f32_e32 v249, v249, v39
	s_waitcnt lgkmcnt(3)
	v_mfma_f32_32x32x16_bf16 v[0:15], v[80:83], v[48:51], v[0:15]
	ds_read_b128 v[80:83], v102 offset:9280
	v_cvt_pk_bf16_f32 v32, v32, v33
	v_cvt_pk_bf16_f32 v33, v34, v35
	v_cvt_pk_bf16_f32 v34, v36, v37
	v_cvt_pk_bf16_f32 v35, v38, v39
	s_waitcnt lgkmcnt(3)
	v_mfma_f32_32x32x16_bf16 v[16:31], v[84:87], v[48:51], v[16:31]
	ds_read_b128 v[84:87], v102 offset:13888
	v_exp_f32_e32 v40, v40
	v_exp_f32_e32 v41, v41
	v_exp_f32_e32 v42, v42
	v_exp_f32_e32 v43, v43
	s_waitcnt lgkmcnt(3)
	v_mfma_f32_32x32x16_bf16 v[0:15], v[104:107], v[56:59], v[0:15]
	ds_read_b128 v[104:107], v102 offset:9312
	v_exp_f32_e32 v44, v44
	v_exp_f32_e32 v45, v45
	v_exp_f32_e32 v46, v46
	v_exp_f32_e32 v47, v47
	s_waitcnt lgkmcnt(3)
	v_mfma_f32_32x32x16_bf16 v[16:31], v[108:111], v[56:59], v[16:31]
	ds_read_b128 v[108:111], v102 offset:13920
	v_add_f32_e32 v198, v198, v40
	v_add_f32_e32 v199, v199, v41
	v_add_f32_e32 v248, v248, v42
	v_add_f32_e32 v249, v249, v43
	v_add_f32_e32 v198, v198, v44
	v_add_f32_e32 v199, v199, v45
	v_add_f32_e32 v248, v248, v46
	v_add_f32_e32 v249, v249, v47
	s_waitcnt lgkmcnt(3)
	v_mfma_f32_32x32x16_bf16 v[0:15], v[80:83], v[32:35], v[0:15]
	v_cvt_pk_bf16_f32 v40, v40, v41
	v_cvt_pk_bf16_f32 v41, v42, v43
	v_cvt_pk_bf16_f32 v42, v44, v45
	v_cvt_pk_bf16_f32 v43, v46, v47
	v_add_u32_e32 v91, s68, v98
	v_add_u32_e32 v92, s68, v170
	s_waitcnt vmcnt(6)
	ds_write_b128 v91, v[120:123]
	ds_write2_b64 v92, v[124:125], v[126:127] offset0:128 offset1:130
	s_waitcnt lgkmcnt(4)
	v_mfma_f32_32x32x16_bf16 v[16:31], v[84:87], v[32:35], v[16:31]
	s_add_i32 s0, s0, 1
	s_cmpk_lt_i32 s0, 62
	s_cselect_b32 s62, 0x4000, 0
	s_cselect_b32 s64, 0x80, 0
	s_mov_b32 s69, s66
	s_mov_b32 s66, s67
	s_mov_b32 s67, s68
	s_mov_b32 s68, s69
	s_waitcnt lgkmcnt(3)
	v_mfma_f32_32x32x16_bf16 v[0:15], v[104:107], v[40:43], v[0:15]
	s_waitcnt lgkmcnt(2)
	v_mfma_f32_32x32x16_bf16 v[16:31], v[108:111], v[40:43], v[16:31]
	s_waitcnt lgkmcnt(0)
	global_load_dwordx4 v[120:123], v[94:95], off
	global_load_dwordx4 v[124:127], v[96:97], off
	s_barrier

.Lgqa_rb1:
	ds_read_b128 v[80:83], v101
	ds_read_b128 v[84:87], v101 offset:32
	ds_read_b128 v[104:107], v101 offset:64
	ds_read_b128 v[108:111], v101 offset:96
	v_exp_f32_e32 v232, v232
	v_exp_f32_e32 v233, v233
	v_exp_f32_e32 v234, v234
	v_exp_f32_e32 v235, v235
	v_exp_f32_e32 v236, v236
	v_exp_f32_e32 v237, v237
	v_exp_f32_e32 v238, v238
	v_exp_f32_e32 v239, v239
	v_add_f32_e32 v198, v198, v232
	v_add_f32_e32 v199, v199, v233
	v_add_f32_e32 v248, v248, v234
	v_add_f32_e32 v249, v249, v235
	v_add_f32_e32 v198, v198, v236
	v_add_f32_e32 v199, v199, v237
	v_add_f32_e32 v248, v248, v238
	v_add_f32_e32 v249, v249, v239
	s_waitcnt lgkmcnt(3)
	v_mfma_f32_32x32x16_bf16 v[48:63], v[80:83], v[76:79], v[182:197]
	ds_read_b128 v[80:83], v101 offset:4608
	v_cvt_pk_bf16_f32 v232, v232, v233
	v_cvt_pk_bf16_f32 v233, v234, v235
	v_cvt_pk_bf16_f32 v234, v236, v237
	v_cvt_pk_bf16_f32 v235, v238, v239
	s_waitcnt lgkmcnt(3)
	v_mfma_f32_32x32x16_bf16 v[48:63], v[84:87], v[72:75], v[48:63]
	ds_read_b128 v[84:87], v101 offset:4640
	v_exp_f32_e32 v240, v240
	v_exp_f32_e32 v241, v241
	v_exp_f32_e32 v242, v242
	v_exp_f32_e32 v243, v243
	s_waitcnt lgkmcnt(3)
	v_mfma_f32_32x32x16_bf16 v[48:63], v[104:107], v[68:71], v[48:63]
	ds_read_b128 v[104:107], v101 offset:4672
	v_exp_f32_e32 v244, v244
	v_exp_f32_e32 v245, v245
	v_exp_f32_e32 v246, v246
	v_exp_f32_e32 v247, v247
	s_waitcnt lgkmcnt(3)
	v_mfma_f32_32x32x16_bf16 v[48:63], v[108:111], v[64:67], v[48:63]
	ds_read_b128 v[108:111], v101 offset:4704
	v_add_f32_e32 v198, v198, v240
	v_add_f32_e32 v199, v199, v241
	v_add_f32_e32 v248, v248, v242
	v_add_f32_e32 v249, v249, v243
	v_add_f32_e32 v198, v198, v244
	v_add_f32_e32 v199, v199, v245
	v_add_f32_e32 v248, v248, v246
	v_add_f32_e32 v249, v249, v247
	s_waitcnt lgkmcnt(3)
	v_mfma_f32_32x32x16_bf16 v[32:47], v[80:83], v[76:79], v[182:197]
	ds_read_b128 v[80:83], v102 offset:9216
	v_cvt_pk_bf16_f32 v240, v240, v241
	v_cvt_pk_bf16_f32 v241, v242, v243
	v_cvt_pk_bf16_f32 v242, v244, v245
	v_cvt_pk_bf16_f32 v243, v246, v247
	s_waitcnt lgkmcnt(3)
	v_mfma_f32_32x32x16_bf16 v[32:47], v[84:87], v[72:75], v[32:47]
	ds_read_b128 v[84:87], v102 offset:13824
	v_exp_f32_e32 v216, v216
	v_exp_f32_e32 v217, v217
	v_exp_f32_e32 v218, v218
	v_exp_f32_e32 v219, v219
	s_waitcnt lgkmcnt(3)
	v_mfma_f32_32x32x16_bf16 v[32:47], v[104:107], v[68:71], v[32:47]
	ds_read_b128 v[104:107], v102 offset:9248
	v_exp_f32_e32 v220, v220
	v_exp_f32_e32 v221, v221
	v_exp_f32_e32 v222, v222
	v_exp_f32_e32 v223, v223
	s_waitcnt lgkmcnt(3)
	v_mfma_f32_32x32x16_bf16 v[32:47], v[108:111], v[64:67], v[32:47]
	ds_read_b128 v[108:111], v102 offset:13856
	v_add_f32_e32 v198, v198, v216
	v_add_f32_e32 v199, v199, v217
	v_add_f32_e32 v248, v248, v218
	v_add_f32_e32 v249, v249, v219
	v_add_f32_e32 v198, v198, v220
	v_add_f32_e32 v199, v199, v221
	v_add_f32_e32 v248, v248, v222
	v_add_f32_e32 v249, v249, v223
	s_waitcnt lgkmcnt(3)
	v_mfma_f32_32x32x16_bf16 v[0:15], v[80:83], v[232:235], v[0:15]
	ds_read_b128 v[80:83], v102 offset:9280
	v_cvt_pk_bf16_f32 v216, v216, v217
	v_cvt_pk_bf16_f32 v217, v218, v219
	v_cvt_pk_bf16_f32 v218, v220, v221
	v_cvt_pk_bf16_f32 v219, v222, v223
	s_waitcnt lgkmcnt(3)
	v_mfma_f32_32x32x16_bf16 v[16:31], v[84:87], v[232:235], v[16:31]
	ds_read_b128 v[84:87], v102 offset:13888
	v_exp_f32_e32 v224, v224
	v_exp_f32_e32 v225, v225
	v_exp_f32_e32 v226, v226
	v_exp_f32_e32 v227, v227
	s_waitcnt lgkmcnt(3)
	v_mfma_f32_32x32x16_bf16 v[0:15], v[104:107], v[240:243], v[0:15]
	ds_read_b128 v[104:107], v102 offset:9312
	v_exp_f32_e32 v228, v228
	v_exp_f32_e32 v229, v229
	v_exp_f32_e32 v230, v230
	v_exp_f32_e32 v231, v231
	s_waitcnt lgkmcnt(3)
	v_mfma_f32_32x32x16_bf16 v[16:31], v[108:111], v[240:243], v[16:31]
	ds_read_b128 v[108:111], v102 offset:13920
	v_add_f32_e32 v198, v198, v224
	v_add_f32_e32 v199, v199, v225
	v_add_f32_e32 v248, v248, v226
	v_add_f32_e32 v249, v249, v227
	v_add_f32_e32 v198, v198, v228
	v_add_f32_e32 v199, v199, v229
	v_add_f32_e32 v248, v248, v230
	v_add_f32_e32 v249, v249, v231
	s_waitcnt lgkmcnt(3)
	v_mfma_f32_32x32x16_bf16 v[0:15], v[80:83], v[216:219], v[0:15]
	v_cvt_pk_bf16_f32 v224, v224, v225
	v_cvt_pk_bf16_f32 v225, v226, v227
	v_cvt_pk_bf16_f32 v226, v228, v229
	v_cvt_pk_bf16_f32 v227, v230, v231
	v_add_u32_e32 v91, s68, v98
	v_add_u32_e32 v92, s68, v170
	s_waitcnt vmcnt(6)
	ds_write_b128 v91, v[208:211]
	ds_write2_b64 v92, v[212:213], v[214:215] offset0:128 offset1:130
	s_waitcnt lgkmcnt(4)
	v_mfma_f32_32x32x16_bf16 v[16:31], v[84:87], v[216:219], v[16:31]
	s_add_i32 s0, s0, 1
	s_cmpk_lt_i32 s0, 62
	s_cselect_b32 s62, 0x4000, 0
	s_cselect_b32 s64, 0x80, 0
	s_mov_b32 s69, s66
	s_mov_b32 s66, s67
	s_mov_b32 s67, s68
	s_mov_b32 s68, s69
	s_waitcnt lgkmcnt(3)
	v_mfma_f32_32x32x16_bf16 v[0:15], v[104:107], v[224:227], v[0:15]
	s_waitcnt lgkmcnt(2)
	v_mfma_f32_32x32x16_bf16 v[16:31], v[108:111], v[224:227], v[16:31]
	s_waitcnt lgkmcnt(0)
	global_load_dwordx4 v[208:211], v[94:95], off
	global_load_dwordx4 v[212:215], v[96:97], off
	s_barrier

.Lgqa_rb2:
	ds_read_b128 v[80:83], v101
	ds_read_b128 v[84:87], v101 offset:32
	ds_read_b128 v[104:107], v101 offset:64
	ds_read_b128 v[108:111], v101 offset:96
	v_exp_f32_e32 v48, v48
	v_exp_f32_e32 v49, v49
	v_exp_f32_e32 v50, v50
	v_exp_f32_e32 v51, v51
	v_exp_f32_e32 v52, v52
	v_exp_f32_e32 v53, v53
	v_exp_f32_e32 v54, v54
	v_exp_f32_e32 v55, v55
	v_add_f32_e32 v198, v198, v48
	v_add_f32_e32 v199, v199, v49
	v_add_f32_e32 v248, v248, v50
	v_add_f32_e32 v249, v249, v51
	v_add_f32_e32 v198, v198, v52
	v_add_f32_e32 v199, v199, v53
	v_add_f32_e32 v248, v248, v54
	v_add_f32_e32 v249, v249, v55
	s_waitcnt lgkmcnt(3)
	v_mfma_f32_32x32x16_bf16 v[232:247], v[80:83], v[76:79], v[182:197]
	ds_read_b128 v[80:83], v101 offset:4608
	v_cvt_pk_bf16_f32 v48, v48, v49
	v_cvt_pk_bf16_f32 v49, v50, v51
	v_cvt_pk_bf16_f32 v50, v52, v53
	v_cvt_pk_bf16_f32 v51, v54, v55
	s_waitcnt lgkmcnt(3)
	v_mfma_f32_32x32x16_bf16 v[232:247], v[84:87], v[72:75], v[232:247]
	ds_read_b128 v[84:87], v101 offset:4640
	v_exp_f32_e32 v56, v56
	v_exp_f32_e32 v57, v57
	v_exp_f32_e32 v58, v58
	v_exp_f32_e32 v59, v59
	s_waitcnt lgkmcnt(3)
	v_mfma_f32_32x32x16_bf16 v[232:247], v[104:107], v[68:71], v[232:247]
	ds_read_b128 v[104:107], v101 offset:4672
	v_exp_f32_e32 v60, v60
	v_exp_f32_e32 v61, v61
	v_exp_f32_e32 v62, v62
	v_exp_f32_e32 v63, v63
	s_waitcnt lgkmcnt(3)
	v_mfma_f32_32x32x16_bf16 v[232:247], v[108:111], v[64:67], v[232:247]
	ds_read_b128 v[108:111], v101 offset:4704
	v_add_f32_e32 v198, v198, v56
	v_add_f32_e32 v199, v199, v57
	v_add_f32_e32 v248, v248, v58
	v_add_f32_e32 v249, v249, v59
	v_add_f32_e32 v198, v198, v60
	v_add_f32_e32 v199, v199, v61
	v_add_f32_e32 v248, v248, v62
	v_add_f32_e32 v249, v249, v63
	s_waitcnt lgkmcnt(3)
	v_mfma_f32_32x32x16_bf16 v[216:231], v[80:83], v[76:79], v[182:197]
	ds_read_b128 v[80:83], v102 offset:9216
	v_cvt_pk_bf16_f32 v56, v56, v57
	v_cvt_pk_bf16_f32 v57, v58, v59
	v_cvt_pk_bf16_f32 v58, v60, v61
	v_cvt_pk_bf16_f32 v59, v62, v63
	s_waitcnt lgkmcnt(3)
	v_mfma_f32_32x32x16_bf16 v[216:231], v[84:87], v[72:75], v[216:231]
	ds_read_b128 v[84:87], v102 offset:13824
	v_exp_f32_e32 v32, v32
	v_exp_f32_e32 v33, v33
	v_exp_f32_e32 v34, v34
	v_exp_f32_e32 v35, v35
	s_waitcnt lgkmcnt(3)
	v_mfma_f32_32x32x16_bf16 v[216:231], v[104:107], v[68:71], v[216:231]
	ds_read_b128 v[104:107], v102 offset:9248
	v_exp_f32_e32 v36, v36
	v_exp_f32_e32 v37, v37
	v_exp_f32_e32 v38, v38
	v_exp_f32_e32 v39, v39
	s_waitcnt lgkmcnt(3)
	v_mfma_f32_32x32x16_bf16 v[216:231], v[108:111], v[64:67], v[216:231]
	ds_read_b128 v[108:111], v102 offset:13856
	v_add_f32_e32 v198, v198, v32
	v_add_f32_e32 v199, v199, v33
	v_add_f32_e32 v248, v248, v34
	v_add_f32_e32 v249, v249, v35
	v_add_f32_e32 v198, v198, v36
	v_add_f32_e32 v199, v199, v37
	v_add_f32_e32 v248, v248, v38
	v_add_f32_e32 v249, v249, v39
	s_waitcnt lgkmcnt(3)
	v_mfma_f32_32x32x16_bf16 v[0:15], v[80:83], v[48:51], v[0:15]
	ds_read_b128 v[80:83], v102 offset:9280
	v_cvt_pk_bf16_f32 v32, v32, v33
	v_cvt_pk_bf16_f32 v33, v34, v35
	v_cvt_pk_bf16_f32 v34, v36, v37
	v_cvt_pk_bf16_f32 v35, v38, v39
	s_waitcnt lgkmcnt(3)
	v_mfma_f32_32x32x16_bf16 v[16:31], v[84:87], v[48:51], v[16:31]
	ds_read_b128 v[84:87], v102 offset:13888
	v_exp_f32_e32 v40, v40
	v_exp_f32_e32 v41, v41
	v_exp_f32_e32 v42, v42
	v_exp_f32_e32 v43, v43
	s_waitcnt lgkmcnt(3)
	v_mfma_f32_32x32x16_bf16 v[0:15], v[104:107], v[56:59], v[0:15]
	ds_read_b128 v[104:107], v102 offset:9312
	v_exp_f32_e32 v44, v44
	v_exp_f32_e32 v45, v45
	v_exp_f32_e32 v46, v46
	v_exp_f32_e32 v47, v47
	s_waitcnt lgkmcnt(3)
	v_mfma_f32_32x32x16_bf16 v[16:31], v[108:111], v[56:59], v[16:31]
	ds_read_b128 v[108:111], v102 offset:13920
	v_add_f32_e32 v198, v198, v40
	v_add_f32_e32 v199, v199, v41
	v_add_f32_e32 v248, v248, v42
	v_add_f32_e32 v249, v249, v43
	v_add_f32_e32 v198, v198, v44
	v_add_f32_e32 v199, v199, v45
	v_add_f32_e32 v248, v248, v46
	v_add_f32_e32 v249, v249, v47
	s_waitcnt lgkmcnt(3)
	v_mfma_f32_32x32x16_bf16 v[0:15], v[80:83], v[32:35], v[0:15]
	v_cvt_pk_bf16_f32 v40, v40, v41
	v_cvt_pk_bf16_f32 v41, v42, v43
	v_cvt_pk_bf16_f32 v42, v44, v45
	v_cvt_pk_bf16_f32 v43, v46, v47
	v_add_u32_e32 v91, s68, v98
	v_add_u32_e32 v92, s68, v170
	s_waitcnt vmcnt(6)
	ds_write_b128 v91, v[200:203]
	ds_write2_b64 v92, v[204:205], v[206:207] offset0:128 offset1:130
	s_waitcnt lgkmcnt(4)
	v_mfma_f32_32x32x16_bf16 v[16:31], v[84:87], v[32:35], v[16:31]
	s_add_i32 s0, s0, 1
	s_cmpk_lt_i32 s0, 62
	s_cselect_b32 s62, 0x4000, 0
	s_cselect_b32 s64, 0x80, 0
	s_mov_b32 s69, s66
	s_mov_b32 s66, s67
	s_mov_b32 s67, s68
	s_mov_b32 s68, s69
	s_waitcnt lgkmcnt(3)
	v_mfma_f32_32x32x16_bf16 v[0:15], v[104:107], v[40:43], v[0:15]
	s_waitcnt lgkmcnt(2)
	v_mfma_f32_32x32x16_bf16 v[16:31], v[108:111], v[40:43], v[16:31]
	s_waitcnt lgkmcnt(0)
	global_load_dwordx4 v[200:203], v[94:95], off
	global_load_dwordx4 v[204:207], v[96:97], off
	s_barrier

.Lgqa_rb3:
	ds_read_b128 v[80:83], v101
	ds_read_b128 v[84:87], v101 offset:32
	ds_read_b128 v[104:107], v101 offset:64
	ds_read_b128 v[108:111], v101 offset:96
	v_exp_f32_e32 v232, v232
	v_exp_f32_e32 v233, v233
	v_exp_f32_e32 v234, v234
	v_exp_f32_e32 v235, v235
	v_exp_f32_e32 v236, v236
	v_exp_f32_e32 v237, v237
	v_exp_f32_e32 v238, v238
	v_exp_f32_e32 v239, v239
	v_add_f32_e32 v198, v198, v232
	v_add_f32_e32 v199, v199, v233
	v_add_f32_e32 v248, v248, v234
	v_add_f32_e32 v249, v249, v235
	v_add_f32_e32 v198, v198, v236
	v_add_f32_e32 v199, v199, v237
	v_add_f32_e32 v248, v248, v238
	v_add_f32_e32 v249, v249, v239
	s_waitcnt lgkmcnt(3)
	v_mfma_f32_32x32x16_bf16 v[48:63], v[80:83], v[76:79], v[182:197]
	ds_read_b128 v[80:83], v101 offset:4608
	v_cvt_pk_bf16_f32 v232, v232, v233
	v_cvt_pk_bf16_f32 v233, v234, v235
	v_cvt_pk_bf16_f32 v234, v236, v237
	v_cvt_pk_bf16_f32 v235, v238, v239
	s_waitcnt lgkmcnt(3)
	v_mfma_f32_32x32x16_bf16 v[48:63], v[84:87], v[72:75], v[48:63]
	ds_read_b128 v[84:87], v101 offset:4640
	v_exp_f32_e32 v240, v240
	v_exp_f32_e32 v241, v241
	v_exp_f32_e32 v242, v242
	v_exp_f32_e32 v243, v243
	s_waitcnt lgkmcnt(3)
	v_mfma_f32_32x32x16_bf16 v[48:63], v[104:107], v[68:71], v[48:63]
	ds_read_b128 v[104:107], v101 offset:4672
	v_exp_f32_e32 v244, v244
	v_exp_f32_e32 v245, v245
	v_exp_f32_e32 v246, v246
	v_exp_f32_e32 v247, v247
	s_waitcnt lgkmcnt(3)
	v_mfma_f32_32x32x16_bf16 v[48:63], v[108:111], v[64:67], v[48:63]
	ds_read_b128 v[108:111], v101 offset:4704
	v_add_f32_e32 v198, v198, v240
	v_add_f32_e32 v199, v199, v241
	v_add_f32_e32 v248, v248, v242
	v_add_f32_e32 v249, v249, v243
	v_add_f32_e32 v198, v198, v244
	v_add_f32_e32 v199, v199, v245
	v_add_f32_e32 v248, v248, v246
	v_add_f32_e32 v249, v249, v247
	s_waitcnt lgkmcnt(3)
	v_mfma_f32_32x32x16_bf16 v[32:47], v[80:83], v[76:79], v[182:197]
	ds_read_b128 v[80:83], v102 offset:9216
	v_cvt_pk_bf16_f32 v240, v240, v241
	v_cvt_pk_bf16_f32 v241, v242, v243
	v_cvt_pk_bf16_f32 v242, v244, v245
	v_cvt_pk_bf16_f32 v243, v246, v247
	s_waitcnt lgkmcnt(3)
	v_mfma_f32_32x32x16_bf16 v[32:47], v[84:87], v[72:75], v[32:47]
	ds_read_b128 v[84:87], v102 offset:13824
	v_exp_f32_e32 v216, v216
	v_exp_f32_e32 v217, v217
	v_exp_f32_e32 v218, v218
	v_exp_f32_e32 v219, v219
	s_waitcnt lgkmcnt(3)
	v_mfma_f32_32x32x16_bf16 v[32:47], v[104:107], v[68:71], v[32:47]
	ds_read_b128 v[104:107], v102 offset:9248
	v_exp_f32_e32 v220, v220
	v_exp_f32_e32 v221, v221
	v_exp_f32_e32 v222, v222
	v_exp_f32_e32 v223, v223
	s_waitcnt lgkmcnt(3)
	v_mfma_f32_32x32x16_bf16 v[32:47], v[108:111], v[64:67], v[32:47]
	ds_read_b128 v[108:111], v102 offset:13856
	v_add_f32_e32 v198, v198, v216
	v_add_f32_e32 v199, v199, v217
	v_add_f32_e32 v248, v248, v218
	v_add_f32_e32 v249, v249, v219
	v_add_f32_e32 v198, v198, v220
	v_add_f32_e32 v199, v199, v221
	v_add_f32_e32 v248, v248, v222
	v_add_f32_e32 v249, v249, v223
	s_waitcnt lgkmcnt(3)
	v_mfma_f32_32x32x16_bf16 v[0:15], v[80:83], v[232:235], v[0:15]
	ds_read_b128 v[80:83], v102 offset:9280
	v_cvt_pk_bf16_f32 v216, v216, v217
	v_cvt_pk_bf16_f32 v217, v218, v219
	v_cvt_pk_bf16_f32 v218, v220, v221
	v_cvt_pk_bf16_f32 v219, v222, v223
	s_waitcnt lgkmcnt(3)
	v_mfma_f32_32x32x16_bf16 v[16:31], v[84:87], v[232:235], v[16:31]
	ds_read_b128 v[84:87], v102 offset:13888
	v_exp_f32_e32 v224, v224
	v_exp_f32_e32 v225, v225
	v_exp_f32_e32 v226, v226
	v_exp_f32_e32 v227, v227
	s_waitcnt lgkmcnt(3)
	v_mfma_f32_32x32x16_bf16 v[0:15], v[104:107], v[240:243], v[0:15]
	ds_read_b128 v[104:107], v102 offset:9312
	v_exp_f32_e32 v228, v228
	v_exp_f32_e32 v229, v229
	v_exp_f32_e32 v230, v230
	v_exp_f32_e32 v231, v231
	s_waitcnt lgkmcnt(3)
	v_mfma_f32_32x32x16_bf16 v[16:31], v[108:111], v[240:243], v[16:31]
	ds_read_b128 v[108:111], v102 offset:13920
	v_add_f32_e32 v198, v198, v224
	v_add_f32_e32 v199, v199, v225
	v_add_f32_e32 v248, v248, v226
	v_add_f32_e32 v249, v249, v227
	v_add_f32_e32 v198, v198, v228
	v_add_f32_e32 v199, v199, v229
	v_add_f32_e32 v248, v248, v230
	v_add_f32_e32 v249, v249, v231
	s_waitcnt lgkmcnt(3)
	v_mfma_f32_32x32x16_bf16 v[0:15], v[80:83], v[216:219], v[0:15]
	v_cvt_pk_bf16_f32 v224, v224, v225
	v_cvt_pk_bf16_f32 v225, v226, v227
	v_cvt_pk_bf16_f32 v226, v228, v229
	v_cvt_pk_bf16_f32 v227, v230, v231
	v_add_u32_e32 v91, s68, v98
	v_add_u32_e32 v92, s68, v170
	s_waitcnt vmcnt(6)
	ds_write_b128 v91, v[112:115]
	ds_write2_b64 v92, v[116:117], v[118:119] offset0:128 offset1:130
	s_waitcnt lgkmcnt(4)
	v_mfma_f32_32x32x16_bf16 v[16:31], v[84:87], v[216:219], v[16:31]
	s_add_i32 s0, s0, 1
	s_cmpk_lt_i32 s0, 62
	s_cselect_b32 s62, 0x4000, 0
	s_cselect_b32 s64, 0x80, 0
	s_mov_b32 s69, s66
	s_mov_b32 s66, s67
	s_mov_b32 s67, s68
	s_mov_b32 s68, s69
	s_waitcnt lgkmcnt(3)
	v_mfma_f32_32x32x16_bf16 v[0:15], v[104:107], v[224:227], v[0:15]
	s_waitcnt lgkmcnt(2)
	v_mfma_f32_32x32x16_bf16 v[16:31], v[108:111], v[224:227], v[16:31]
	s_waitcnt lgkmcnt(0)
	global_load_dwordx4 v[112:115], v[94:95], off
	global_load_dwordx4 v[116:119], v[96:97], off
	s_barrier
	s_cmpk_eq_i32 s0, 0x44
	s_cbranch_scc1 .LBB0_1175
	s_branch .Lgqa_c0
.Lgqa_rare0:
	v_frexp_exp_i32_f32_e32 v92, v91
	v_sub_u32_e32 v181, 0, v92
	v_cvt_f32_i32_e32 v179, v92
	v_ldexp_f32 v178, 1.0, v181
	v_pk_mul_f32 v[0:1], v[0:1], v[178:179] op_sel_hi:[1,0]
	v_pk_mul_f32 v[2:3], v[2:3], v[178:179] op_sel_hi:[1,0]
	v_pk_mul_f32 v[4:5], v[4:5], v[178:179] op_sel_hi:[1,0]
	v_pk_mul_f32 v[6:7], v[6:7], v[178:179] op_sel_hi:[1,0]
	v_pk_mul_f32 v[8:9], v[8:9], v[178:179] op_sel_hi:[1,0]
	v_pk_mul_f32 v[10:11], v[10:11], v[178:179] op_sel_hi:[1,0]
	v_pk_mul_f32 v[12:13], v[12:13], v[178:179] op_sel_hi:[1,0]
	v_pk_mul_f32 v[14:15], v[14:15], v[178:179] op_sel_hi:[1,0]
	v_pk_mul_f32 v[16:17], v[16:17], v[178:179] op_sel_hi:[1,0]
	v_pk_mul_f32 v[18:19], v[18:19], v[178:179] op_sel_hi:[1,0]
	v_pk_mul_f32 v[20:21], v[20:21], v[178:179] op_sel_hi:[1,0]
	v_pk_mul_f32 v[22:23], v[22:23], v[178:179] op_sel_hi:[1,0]
	v_pk_mul_f32 v[24:25], v[24:25], v[178:179] op_sel_hi:[1,0]
	v_pk_mul_f32 v[26:27], v[26:27], v[178:179] op_sel_hi:[1,0]
	v_pk_mul_f32 v[28:29], v[28:29], v[178:179] op_sel_hi:[1,0]
	v_pk_mul_f32 v[30:31], v[30:31], v[178:179] op_sel_hi:[1,0]
	v_pk_mul_f32 v[198:199], v[198:199], v[178:179] op_sel_hi:[1,0]
	v_pk_mul_f32 v[248:249], v[248:249], v[178:179] op_sel_hi:[1,0]
	v_sub_f32_e32 v182, v182, v179
	v_sub_f32_e32 v183, v183, v179
	v_sub_f32_e32 v184, v184, v179
	v_sub_f32_e32 v185, v185, v179
	v_sub_f32_e32 v186, v186, v179
	v_sub_f32_e32 v187, v187, v179
	v_sub_f32_e32 v188, v188, v179
	v_sub_f32_e32 v189, v189, v179
	v_sub_f32_e32 v190, v190, v179
	v_sub_f32_e32 v191, v191, v179
	v_sub_f32_e32 v192, v192, v179
	v_sub_f32_e32 v193, v193, v179
	v_sub_f32_e32 v194, v194, v179
	v_sub_f32_e32 v195, v195, v179
	v_sub_f32_e32 v196, v196, v179
	v_sub_f32_e32 v197, v197, v179
	v_sub_f32_e32 v48, v48, v179
	v_sub_f32_e32 v49, v49, v179
	v_sub_f32_e32 v50, v50, v179
	v_sub_f32_e32 v51, v51, v179
	v_sub_f32_e32 v52, v52, v179
	v_sub_f32_e32 v53, v53, v179
	v_sub_f32_e32 v54, v54, v179
	v_sub_f32_e32 v55, v55, v179
	v_sub_f32_e32 v56, v56, v179
	v_sub_f32_e32 v57, v57, v179
	v_sub_f32_e32 v58, v58, v179
	v_sub_f32_e32 v59, v59, v179
	v_sub_f32_e32 v60, v60, v179
	v_sub_f32_e32 v61, v61, v179
	v_sub_f32_e32 v62, v62, v179
	v_sub_f32_e32 v63, v63, v179
	v_sub_f32_e32 v32, v32, v179
	v_sub_f32_e32 v33, v33, v179
	v_sub_f32_e32 v34, v34, v179
	v_sub_f32_e32 v35, v35, v179
	v_sub_f32_e32 v36, v36, v179
	v_sub_f32_e32 v37, v37, v179
	v_sub_f32_e32 v38, v38, v179
	v_sub_f32_e32 v39, v39, v179
	v_sub_f32_e32 v40, v40, v179
	v_sub_f32_e32 v41, v41, v179
	v_sub_f32_e32 v42, v42, v179
	v_sub_f32_e32 v43, v43, v179
	v_sub_f32_e32 v44, v44, v179
	v_sub_f32_e32 v45, v45, v179
	v_sub_f32_e32 v46, v46, v179
	v_sub_f32_e32 v47, v47, v179
	s_branch .Lgqa_rb0
.Lgqa_rare1:
	v_frexp_exp_i32_f32_e32 v92, v91
	v_sub_u32_e32 v181, 0, v92
	v_cvt_f32_i32_e32 v179, v92
	v_ldexp_f32 v178, 1.0, v181
	v_pk_mul_f32 v[0:1], v[0:1], v[178:179] op_sel_hi:[1,0]
	v_pk_mul_f32 v[2:3], v[2:3], v[178:179] op_sel_hi:[1,0]
	v_pk_mul_f32 v[4:5], v[4:5], v[178:179] op_sel_hi:[1,0]
	v_pk_mul_f32 v[6:7], v[6:7], v[178:179] op_sel_hi:[1,0]
	v_pk_mul_f32 v[8:9], v[8:9], v[178:179] op_sel_hi:[1,0]
	v_pk_mul_f32 v[10:11], v[10:11], v[178:179] op_sel_hi:[1,0]
	v_pk_mul_f32 v[12:13], v[12:13], v[178:179] op_sel_hi:[1,0]
	v_pk_mul_f32 v[14:15], v[14:15], v[178:179] op_sel_hi:[1,0]
	v_pk_mul_f32 v[16:17], v[16:17], v[178:179] op_sel_hi:[1,0]
	v_pk_mul_f32 v[18:19], v[18:19], v[178:179] op_sel_hi:[1,0]
	v_pk_mul_f32 v[20:21], v[20:21], v[178:179] op_sel_hi:[1,0]
	v_pk_mul_f32 v[22:23], v[22:23], v[178:179] op_sel_hi:[1,0]
	v_pk_mul_f32 v[24:25], v[24:25], v[178:179] op_sel_hi:[1,0]
	v_pk_mul_f32 v[26:27], v[26:27], v[178:179] op_sel_hi:[1,0]
	v_pk_mul_f32 v[28:29], v[28:29], v[178:179] op_sel_hi:[1,0]
	v_pk_mul_f32 v[30:31], v[30:31], v[178:179] op_sel_hi:[1,0]
	v_pk_mul_f32 v[198:199], v[198:199], v[178:179] op_sel_hi:[1,0]
	v_pk_mul_f32 v[248:249], v[248:249], v[178:179] op_sel_hi:[1,0]
	v_sub_f32_e32 v182, v182, v179
	v_sub_f32_e32 v183, v183, v179
	v_sub_f32_e32 v184, v184, v179
	v_sub_f32_e32 v185, v185, v179
	v_sub_f32_e32 v186, v186, v179
	v_sub_f32_e32 v187, v187, v179
	v_sub_f32_e32 v188, v188, v179
	v_sub_f32_e32 v189, v189, v179
	v_sub_f32_e32 v190, v190, v179
	v_sub_f32_e32 v191, v191, v179
	v_sub_f32_e32 v192, v192, v179
	v_sub_f32_e32 v193, v193, v179
	v_sub_f32_e32 v194, v194, v179
	v_sub_f32_e32 v195, v195, v179
	v_sub_f32_e32 v196, v196, v179
	v_sub_f32_e32 v197, v197, v179
	v_sub_f32_e32 v232, v232, v179
	v_sub_f32_e32 v233, v233, v179
	v_sub_f32_e32 v234, v234, v179
	v_sub_f32_e32 v235, v235, v179
	v_sub_f32_e32 v236, v236, v179
	v_sub_f32_e32 v237, v237, v179
	v_sub_f32_e32 v238, v238, v179
	v_sub_f32_e32 v239, v239, v179
	v_sub_f32_e32 v240, v240, v179
	v_sub_f32_e32 v241, v241, v179
	v_sub_f32_e32 v242, v242, v179
	v_sub_f32_e32 v243, v243, v179
	v_sub_f32_e32 v244, v244, v179
	v_sub_f32_e32 v245, v245, v179
	v_sub_f32_e32 v246, v246, v179
	v_sub_f32_e32 v247, v247, v179
	v_sub_f32_e32 v216, v216, v179
	v_sub_f32_e32 v217, v217, v179
	v_sub_f32_e32 v218, v218, v179
	v_sub_f32_e32 v219, v219, v179
	v_sub_f32_e32 v220, v220, v179
	v_sub_f32_e32 v221, v221, v179
	v_sub_f32_e32 v222, v222, v179
	v_sub_f32_e32 v223, v223, v179
	v_sub_f32_e32 v224, v224, v179
	v_sub_f32_e32 v225, v225, v179
	v_sub_f32_e32 v226, v226, v179
	v_sub_f32_e32 v227, v227, v179
	v_sub_f32_e32 v228, v228, v179
	v_sub_f32_e32 v229, v229, v179
	v_sub_f32_e32 v230, v230, v179
	v_sub_f32_e32 v231, v231, v179
	s_branch .Lgqa_rb1
